# grid-barrier poll loops without s_sleep 1 (16 sites, replaced by s_nop 0)
# speedup vs baseline: 1.0070x; 1.0070x over previous
.LBB0_16:
	s_nop 0
	global_load_dword v2, v0, s[4:5] offset:32 sc1
	s_waitcnt vmcnt(0)
	v_and_b32_e32 v2, 0xffff0000, v2
	v_cmp_ne_u32_e32 vcc, v2, v1
	s_or_b64 s[6:7], vcc, s[6:7]
	s_andn2_b64 exec, exec, s[6:7]
	s_cbranch_execnz .LBB0_16

.LBB0_154:
	v_readlane_b32 s48, v251, 4
	v_readlane_b32 s60, v251, 16
	v_readlane_b32 s61, v251, 17
	v_readlane_b32 s62, v251, 18
	v_readlane_b32 s63, v251, 19
	s_mov_b64 s[28:29], s[60:61]
	s_mov_b64 s[30:31], s[62:63]
	global_load_dword v10, v16, s[30:31] offset:1024 sc1
	global_load_dword v0, v16, s[30:31] offset:1280 sc1
	global_load_dword v1, v16, s[30:31] offset:1536 sc1
	global_load_dword v2, v16, s[30:31] offset:1792 sc1
	global_load_dword v3, v16, s[30:31] offset:2048 sc1
	global_load_dword v4, v16, s[30:31] offset:2304 sc1
	global_load_dword v5, v16, s[30:31] offset:2560 sc1
	global_load_dword v6, v16, s[30:31] offset:2816 sc1
	global_load_dword v7, v16, s[30:31] offset:3072 sc1
	global_load_dword v8, v16, s[30:31] offset:3328 sc1
	global_load_dword v9, v16, s[30:31] offset:3584 sc1
	global_load_dword v11, v16, s[30:31] offset:3840 sc1
	global_load_dword v12, v16, s[8:9] sc1
	global_load_dword v13, v16, s[10:11] sc1
	global_load_dword v14, v16, s[12:13] sc1
	global_load_dword v15, v16, s[14:15] sc1
	s_mov_b64 s[16:17], -1
	s_mov_b64 s[20:21], -1
	v_readlane_b32 s49, v251, 5
	v_readlane_b32 s50, v251, 6
	v_readlane_b32 s51, v251, 7
	v_readlane_b32 s52, v251, 8
	v_readlane_b32 s53, v251, 9
	v_readlane_b32 s54, v251, 10
	v_readlane_b32 s55, v251, 11
	v_readlane_b32 s56, v251, 12
	v_readlane_b32 s57, v251, 13
	v_readlane_b32 s58, v251, 14
	v_readlane_b32 s59, v251, 15
	s_waitcnt vmcnt(14)
	v_add_u32_e32 v17, v0, v10
	s_waitcnt vmcnt(13)
	v_add_u32_e32 v17, v17, v1
	s_waitcnt vmcnt(12)
	v_add_u32_e32 v17, v17, v2
	s_waitcnt vmcnt(11)
	v_add_u32_e32 v17, v17, v3
	s_waitcnt vmcnt(10)
	v_add_u32_e32 v17, v17, v4
	s_waitcnt vmcnt(9)
	v_add_u32_e32 v17, v17, v5
	s_waitcnt vmcnt(8)
	v_add_u32_e32 v17, v17, v6
	s_waitcnt vmcnt(7)
	v_add_u32_e32 v17, v17, v7
	s_waitcnt vmcnt(6)
	v_add_u32_e32 v17, v17, v8
	s_waitcnt vmcnt(5)
	v_add_u32_e32 v17, v17, v9
	s_waitcnt vmcnt(4)
	v_add_u32_e32 v17, v17, v11
	s_waitcnt vmcnt(3)
	v_add_u32_e32 v17, v17, v12
	s_waitcnt vmcnt(2)
	v_add_u32_e32 v17, v17, v13
	s_waitcnt vmcnt(1)
	v_add_u32_e32 v17, v17, v14
	s_waitcnt vmcnt(0)
	v_add_u32_e32 v17, v17, v15
	v_cmp_eq_u32_e32 vcc, s18, v17
	s_cbranch_vccnz .LBB0_153
	s_and_b32 s16, s24, 0xff
	s_cmp_eq_u32 s16, 0
	s_mov_b64 s[16:17], -1
	s_mov_b64 s[22:23], -1
	s_nop 0
	s_cbranch_scc0 .LBB0_158
	global_load_dword v17, v16, s[4:5] sc1
	s_waitcnt vmcnt(0)
	v_cmp_eq_u32_e32 vcc, 0, v17
	s_cbranch_vccnz .LBB0_160
	s_mov_b64 s[22:23], 0

.LBB0_172:
	s_and_b32 s22, s18, 0xff
	s_mov_b64 s[20:21], -1
	s_cmp_lg_u32 s22, 0
	s_mov_b64 s[24:25], -1
	s_nop 0
	s_cbranch_scc1 .LBB0_175
	global_load_dword v1, v0, s[4:5] sc1
	s_waitcnt vmcnt(0)
	v_cmp_eq_u32_e32 vcc, 0, v1
	s_cbranch_vccnz .LBB0_177
	s_mov_b64 s[24:25], 0
	s_mov_b64 s[22:23], -1

.LBB0_189:
	s_and_b32 s22, s18, 0xff
	s_cmp_lg_u32 s22, 0
	s_mov_b64 s[24:25], -1
	s_nop 0
	s_cbranch_scc1 .LBB0_192
	global_load_dword v1, v0, s[4:5] sc1
	s_waitcnt vmcnt(0)
	v_cmp_eq_u32_e32 vcc, 0, v1
	s_cbranch_vccnz .LBB0_194
	s_mov_b64 s[24:25], 0
	s_mov_b64 s[22:23], -1

.LBB0_329:
	v_readlane_b32 s64, v251, 4
	v_readlane_b32 s76, v251, 16
	v_readlane_b32 s77, v251, 17
	v_readlane_b32 s78, v251, 18
	v_readlane_b32 s79, v251, 19
	s_mov_b64 s[52:53], s[76:77]
	v_readlane_b32 s6, v252, 12
	s_mov_b64 s[54:55], s[78:79]
	v_readlane_b32 s7, v252, 13
	global_load_dword v10, v189, s[54:55] offset:1024 sc1
	global_load_dword v0, v189, s[54:55] offset:1280 sc1
	global_load_dword v1, v189, s[54:55] offset:1536 sc1
	global_load_dword v2, v189, s[54:55] offset:1792 sc1
	global_load_dword v3, v189, s[54:55] offset:2048 sc1
	global_load_dword v4, v189, s[54:55] offset:2304 sc1
	global_load_dword v5, v189, s[54:55] offset:2560 sc1
	global_load_dword v6, v189, s[54:55] offset:2816 sc1
	global_load_dword v7, v189, s[54:55] offset:3072 sc1
	global_load_dword v8, v189, s[54:55] offset:3328 sc1
	global_load_dword v9, v189, s[54:55] offset:3584 sc1
	global_load_dword v11, v189, s[54:55] offset:3840 sc1
	global_load_dword v12, v189, s[6:7] sc1
	v_readlane_b32 s6, v252, 14
	v_readlane_b32 s7, v252, 15
	s_mov_b64 s[20:21], -1
	s_mov_b64 s[30:31], -1
	v_readlane_b32 s65, v251, 5
	v_readlane_b32 s66, v251, 6
	v_readlane_b32 s67, v251, 7
	global_load_dword v13, v189, s[6:7] sc1
	v_readlane_b32 s6, v252, 16
	v_readlane_b32 s7, v252, 17
	v_readlane_b32 s68, v251, 8
	v_readlane_b32 s69, v251, 9
	v_readlane_b32 s70, v251, 10
	v_readlane_b32 s71, v251, 11
	v_readlane_b32 s72, v251, 12
	global_load_dword v14, v189, s[6:7] sc1
	v_readlane_b32 s6, v252, 18
	v_readlane_b32 s7, v252, 19
	v_readlane_b32 s73, v251, 13
	v_readlane_b32 s74, v251, 14
	v_readlane_b32 s75, v251, 15
	s_waitcnt vmcnt(13)
	v_add_u32_e32 v16, v0, v10
	global_load_dword v15, v189, s[6:7] sc1
	s_waitcnt vmcnt(13)
	v_add_u32_e32 v16, v16, v1
	s_waitcnt vmcnt(12)
	v_add_u32_e32 v16, v16, v2
	s_waitcnt vmcnt(11)
	v_add_u32_e32 v16, v16, v3
	s_waitcnt vmcnt(10)
	v_add_u32_e32 v16, v16, v4
	s_waitcnt vmcnt(9)
	v_add_u32_e32 v16, v16, v5
	s_waitcnt vmcnt(8)
	v_add_u32_e32 v16, v16, v6
	s_waitcnt vmcnt(7)
	v_add_u32_e32 v16, v16, v7
	s_waitcnt vmcnt(6)
	v_add_u32_e32 v16, v16, v8
	s_waitcnt vmcnt(5)
	v_add_u32_e32 v16, v16, v9
	s_waitcnt vmcnt(4)
	v_add_u32_e32 v16, v16, v11
	s_waitcnt vmcnt(3)
	v_add_u32_e32 v16, v16, v12
	s_waitcnt vmcnt(2)
	v_add_u32_e32 v16, v16, v13
	s_waitcnt vmcnt(1)
	v_add_u32_e32 v16, v16, v14
	s_waitcnt vmcnt(0)
	v_add_u32_e32 v16, v16, v15
	v_cmp_eq_u32_e32 vcc, s36, v16
	s_cbranch_vccnz .LBB0_328
	s_and_b32 s20, s37, 0xff
	s_cmp_eq_u32 s20, 0
	s_mov_b64 s[20:21], -1
	s_mov_b64 s[34:35], -1
	s_nop 0
	s_cbranch_scc0 .LBB0_333
	v_readlane_b32 s6, v252, 10
	v_readlane_b32 s7, v252, 11
	s_nop 4
	global_load_dword v16, v189, s[6:7] sc1
	s_waitcnt vmcnt(0)
	v_cmp_eq_u32_e32 vcc, 0, v16
	s_cbranch_vccnz .LBB0_335
	s_mov_b64 s[34:35], 0

.LBB0_347:
	s_and_b32 s40, s44, 0xff
	s_mov_b64 s[38:39], -1
	s_cmp_lg_u32 s40, 0
	s_mov_b64 s[42:43], -1
	s_nop 0
	s_cbranch_scc1 .LBB0_350
	v_readlane_b32 s6, v252, 10
	v_readlane_b32 s7, v252, 11
	s_nop 4
	global_load_dword v0, v189, s[6:7] sc1
	s_waitcnt vmcnt(0)
	v_cmp_eq_u32_e32 vcc, 0, v0
	s_cbranch_vccnz .LBB0_352
	s_mov_b64 s[42:43], 0
	s_mov_b64 s[40:41], -1

.LBB0_514:
	v_readlane_b32 s64, v251, 4
	v_readlane_b32 s76, v251, 16
	v_readlane_b32 s77, v251, 17
	v_readlane_b32 s78, v251, 18
	v_readlane_b32 s79, v251, 19
	s_mov_b64 s[48:49], s[76:77]
	v_readlane_b32 s6, v252, 12
	s_mov_b64 s[50:51], s[78:79]
	v_readlane_b32 s7, v252, 13
	global_load_dword v10, v189, s[50:51] offset:1024 sc1
	global_load_dword v0, v189, s[50:51] offset:1280 sc1
	global_load_dword v1, v189, s[50:51] offset:1536 sc1
	global_load_dword v2, v189, s[50:51] offset:1792 sc1
	global_load_dword v3, v189, s[50:51] offset:2048 sc1
	global_load_dword v4, v189, s[50:51] offset:2304 sc1
	global_load_dword v5, v189, s[50:51] offset:2560 sc1
	global_load_dword v6, v189, s[50:51] offset:2816 sc1
	global_load_dword v7, v189, s[50:51] offset:3072 sc1
	global_load_dword v8, v189, s[50:51] offset:3328 sc1
	global_load_dword v9, v189, s[50:51] offset:3584 sc1
	global_load_dword v11, v189, s[50:51] offset:3840 sc1
	global_load_dword v12, v189, s[6:7] sc1
	v_readlane_b32 s6, v252, 14
	v_readlane_b32 s7, v252, 15
	s_mov_b64 s[12:13], -1
	s_mov_b64 s[20:21], -1
	v_readlane_b32 s65, v251, 5
	v_readlane_b32 s66, v251, 6
	v_readlane_b32 s67, v251, 7
	global_load_dword v13, v189, s[6:7] sc1
	v_readlane_b32 s6, v252, 16
	v_readlane_b32 s7, v252, 17
	v_readlane_b32 s68, v251, 8
	v_readlane_b32 s69, v251, 9
	v_readlane_b32 s70, v251, 10
	v_readlane_b32 s71, v251, 11
	v_readlane_b32 s72, v251, 12
	global_load_dword v14, v189, s[6:7] sc1
	v_readlane_b32 s6, v252, 18
	v_readlane_b32 s7, v252, 19
	v_readlane_b32 s73, v251, 13
	v_readlane_b32 s74, v251, 14
	v_readlane_b32 s75, v251, 15
	s_waitcnt vmcnt(13)
	v_add_u32_e32 v16, v0, v10
	global_load_dword v15, v189, s[6:7] sc1
	s_waitcnt vmcnt(13)
	v_add_u32_e32 v16, v16, v1
	s_waitcnt vmcnt(12)
	v_add_u32_e32 v16, v16, v2
	s_waitcnt vmcnt(11)
	v_add_u32_e32 v16, v16, v3
	s_waitcnt vmcnt(10)
	v_add_u32_e32 v16, v16, v4
	s_waitcnt vmcnt(9)
	v_add_u32_e32 v16, v16, v5
	s_waitcnt vmcnt(8)
	v_add_u32_e32 v16, v16, v6
	s_waitcnt vmcnt(7)
	v_add_u32_e32 v16, v16, v7
	s_waitcnt vmcnt(6)
	v_add_u32_e32 v16, v16, v8
	s_waitcnt vmcnt(5)
	v_add_u32_e32 v16, v16, v9
	s_waitcnt vmcnt(4)
	v_add_u32_e32 v16, v16, v11
	s_waitcnt vmcnt(3)
	v_add_u32_e32 v16, v16, v12
	s_waitcnt vmcnt(2)
	v_add_u32_e32 v16, v16, v13
	s_waitcnt vmcnt(1)
	v_add_u32_e32 v16, v16, v14
	s_waitcnt vmcnt(0)
	v_add_u32_e32 v16, v16, v15
	v_cmp_eq_u32_e32 vcc, s34, v16
	s_cbranch_vccnz .LBB0_513
	s_and_b32 s12, s35, 0xff
	s_cmp_eq_u32 s12, 0
	s_mov_b64 s[12:13], -1
	s_mov_b64 s[30:31], -1
	s_nop 0
	s_cbranch_scc0 .LBB0_518
	v_readlane_b32 s6, v252, 10
	v_readlane_b32 s7, v252, 11
	s_nop 4
	global_load_dword v16, v189, s[6:7] sc1
	s_waitcnt vmcnt(0)
	v_cmp_eq_u32_e32 vcc, 0, v16
	s_cbranch_vccnz .LBB0_520
	s_mov_b64 s[30:31], 0

.LBB0_532:
	s_and_b32 s38, s42, 0xff
	s_mov_b64 s[36:37], -1
	s_cmp_lg_u32 s38, 0
	s_mov_b64 s[40:41], -1
	s_nop 0
	s_cbranch_scc1 .LBB0_535
	v_readlane_b32 s6, v252, 10
	v_readlane_b32 s7, v252, 11
	s_nop 4
	global_load_dword v0, v189, s[6:7] sc1
	s_waitcnt vmcnt(0)
	v_cmp_eq_u32_e32 vcc, 0, v0
	s_cbranch_vccnz .LBB0_537
	s_mov_b64 s[40:41], 0
	s_mov_b64 s[38:39], -1

.LBB0_670:
	v_readlane_b32 s64, v251, 4
	v_readlane_b32 s76, v251, 16
	v_readlane_b32 s77, v251, 17
	v_readlane_b32 s78, v251, 18
	v_readlane_b32 s79, v251, 19
	s_mov_b64 s[48:49], s[76:77]
	v_readlane_b32 s6, v252, 12
	s_mov_b64 s[50:51], s[78:79]
	v_readlane_b32 s7, v252, 13
	global_load_dword v10, v189, s[50:51] offset:1024 sc1
	global_load_dword v0, v189, s[50:51] offset:1280 sc1
	global_load_dword v1, v189, s[50:51] offset:1536 sc1
	global_load_dword v2, v189, s[50:51] offset:1792 sc1
	global_load_dword v3, v189, s[50:51] offset:2048 sc1
	global_load_dword v4, v189, s[50:51] offset:2304 sc1
	global_load_dword v5, v189, s[50:51] offset:2560 sc1
	global_load_dword v6, v189, s[50:51] offset:2816 sc1
	global_load_dword v7, v189, s[50:51] offset:3072 sc1
	global_load_dword v8, v189, s[50:51] offset:3328 sc1
	global_load_dword v9, v189, s[50:51] offset:3584 sc1
	global_load_dword v11, v189, s[50:51] offset:3840 sc1
	global_load_dword v12, v189, s[6:7] sc1
	v_readlane_b32 s6, v252, 14
	v_readlane_b32 s7, v252, 15
	s_mov_b64 s[30:31], -1
	s_mov_b64 s[34:35], -1
	v_readlane_b32 s65, v251, 5
	v_readlane_b32 s66, v251, 6
	v_readlane_b32 s67, v251, 7
	global_load_dword v13, v189, s[6:7] sc1
	v_readlane_b32 s6, v252, 16
	v_readlane_b32 s7, v252, 17
	v_readlane_b32 s68, v251, 8
	v_readlane_b32 s69, v251, 9
	v_readlane_b32 s70, v251, 10
	v_readlane_b32 s71, v251, 11
	v_readlane_b32 s72, v251, 12
	global_load_dword v14, v189, s[6:7] sc1
	v_readlane_b32 s6, v252, 18
	v_readlane_b32 s7, v252, 19
	v_readlane_b32 s73, v251, 13
	v_readlane_b32 s74, v251, 14
	v_readlane_b32 s75, v251, 15
	s_waitcnt vmcnt(13)
	v_add_u32_e32 v16, v0, v10
	global_load_dword v15, v189, s[6:7] sc1
	s_waitcnt vmcnt(13)
	v_add_u32_e32 v16, v16, v1
	s_waitcnt vmcnt(12)
	v_add_u32_e32 v16, v16, v2
	s_waitcnt vmcnt(11)
	v_add_u32_e32 v16, v16, v3
	s_waitcnt vmcnt(10)
	v_add_u32_e32 v16, v16, v4
	s_waitcnt vmcnt(9)
	v_add_u32_e32 v16, v16, v5
	s_waitcnt vmcnt(8)
	v_add_u32_e32 v16, v16, v6
	s_waitcnt vmcnt(7)
	v_add_u32_e32 v16, v16, v7
	s_waitcnt vmcnt(6)
	v_add_u32_e32 v16, v16, v8
	s_waitcnt vmcnt(5)
	v_add_u32_e32 v16, v16, v9
	s_waitcnt vmcnt(4)
	v_add_u32_e32 v16, v16, v11
	s_waitcnt vmcnt(3)
	v_add_u32_e32 v16, v16, v12
	s_waitcnt vmcnt(2)
	v_add_u32_e32 v16, v16, v13
	s_waitcnt vmcnt(1)
	v_add_u32_e32 v16, v16, v14
	s_waitcnt vmcnt(0)
	v_add_u32_e32 v16, v16, v15
	v_cmp_eq_u32_e32 vcc, s40, v16
	s_cbranch_vccnz .LBB0_669
	s_and_b32 s30, s41, 0xff
	s_cmp_eq_u32 s30, 0
	s_mov_b64 s[30:31], -1
	s_mov_b64 s[38:39], -1
	s_nop 0
	s_cbranch_scc0 .LBB0_674
	v_readlane_b32 s6, v252, 10
	v_readlane_b32 s7, v252, 11
	s_nop 4
	global_load_dword v16, v189, s[6:7] sc1
	s_waitcnt vmcnt(0)
	v_cmp_eq_u32_e32 vcc, 0, v16
	s_cbranch_vccnz .LBB0_676
	s_mov_b64 s[38:39], 0

.LBB0_688:
	s_and_b32 s36, s48, 0xff
	s_mov_b64 s[42:43], -1
	s_cmp_lg_u32 s36, 0
	s_mov_b64 s[46:47], -1
	s_nop 0
	s_cbranch_scc1 .LBB0_691
	v_readlane_b32 s6, v252, 10
	v_readlane_b32 s7, v252, 11
	s_nop 4
	global_load_dword v0, v189, s[6:7] sc1
	s_waitcnt vmcnt(0)
	v_cmp_eq_u32_e32 vcc, 0, v0
	s_cbranch_vccnz .LBB0_693
	s_mov_b64 s[46:47], 0
	s_mov_b64 s[44:45], -1

.LBB0_763:
	v_readlane_b32 s64, v251, 4
	v_readlane_b32 s76, v251, 16
	v_readlane_b32 s77, v251, 17
	v_readlane_b32 s78, v251, 18
	v_readlane_b32 s79, v251, 19
	s_mov_b64 s[48:49], s[76:77]
	v_readlane_b32 s6, v252, 12
	s_mov_b64 s[50:51], s[78:79]
	v_readlane_b32 s7, v252, 13
	global_load_dword v10, v189, s[50:51] offset:1024 sc1
	global_load_dword v0, v189, s[50:51] offset:1280 sc1
	global_load_dword v1, v189, s[50:51] offset:1536 sc1
	global_load_dword v2, v189, s[50:51] offset:1792 sc1
	global_load_dword v3, v189, s[50:51] offset:2048 sc1
	global_load_dword v4, v189, s[50:51] offset:2304 sc1
	global_load_dword v5, v189, s[50:51] offset:2560 sc1
	global_load_dword v6, v189, s[50:51] offset:2816 sc1
	global_load_dword v7, v189, s[50:51] offset:3072 sc1
	global_load_dword v8, v189, s[50:51] offset:3328 sc1
	global_load_dword v9, v189, s[50:51] offset:3584 sc1
	global_load_dword v11, v189, s[50:51] offset:3840 sc1
	global_load_dword v12, v189, s[6:7] sc1
	v_readlane_b32 s6, v252, 14
	v_readlane_b32 s7, v252, 15
	s_mov_b64 s[12:13], -1
	s_mov_b64 s[16:17], -1
	v_readlane_b32 s65, v251, 5
	v_readlane_b32 s66, v251, 6
	v_readlane_b32 s67, v251, 7
	global_load_dword v13, v189, s[6:7] sc1
	v_readlane_b32 s6, v252, 16
	v_readlane_b32 s7, v252, 17
	v_readlane_b32 s68, v251, 8
	v_readlane_b32 s69, v251, 9
	v_readlane_b32 s70, v251, 10
	v_readlane_b32 s71, v251, 11
	v_readlane_b32 s72, v251, 12
	global_load_dword v14, v189, s[6:7] sc1
	v_readlane_b32 s6, v252, 18
	v_readlane_b32 s7, v252, 19
	v_readlane_b32 s73, v251, 13
	v_readlane_b32 s74, v251, 14
	v_readlane_b32 s75, v251, 15
	s_waitcnt vmcnt(13)
	v_add_u32_e32 v16, v0, v10
	global_load_dword v15, v189, s[6:7] sc1
	s_waitcnt vmcnt(13)
	v_add_u32_e32 v16, v16, v1
	s_waitcnt vmcnt(12)
	v_add_u32_e32 v16, v16, v2
	s_waitcnt vmcnt(11)
	v_add_u32_e32 v16, v16, v3
	s_waitcnt vmcnt(10)
	v_add_u32_e32 v16, v16, v4
	s_waitcnt vmcnt(9)
	v_add_u32_e32 v16, v16, v5
	s_waitcnt vmcnt(8)
	v_add_u32_e32 v16, v16, v6
	s_waitcnt vmcnt(7)
	v_add_u32_e32 v16, v16, v7
	s_waitcnt vmcnt(6)
	v_add_u32_e32 v16, v16, v8
	s_waitcnt vmcnt(5)
	v_add_u32_e32 v16, v16, v9
	s_waitcnt vmcnt(4)
	v_add_u32_e32 v16, v16, v11
	s_waitcnt vmcnt(3)
	v_add_u32_e32 v16, v16, v12
	s_waitcnt vmcnt(2)
	v_add_u32_e32 v16, v16, v13
	s_waitcnt vmcnt(1)
	v_add_u32_e32 v16, v16, v14
	s_waitcnt vmcnt(0)
	v_add_u32_e32 v16, v16, v15
	v_cmp_eq_u32_e32 vcc, s22, v16
	s_cbranch_vccnz .LBB0_762
	s_and_b32 s12, s23, 0xff
	s_cmp_eq_u32 s12, 0
	s_mov_b64 s[12:13], -1
	s_mov_b64 s[20:21], -1
	s_nop 0
	s_cbranch_scc0 .LBB0_767
	v_readlane_b32 s6, v252, 10
	v_readlane_b32 s7, v252, 11
	s_nop 4
	global_load_dword v16, v189, s[6:7] sc1
	s_waitcnt vmcnt(0)
	v_cmp_eq_u32_e32 vcc, 0, v16
	s_cbranch_vccnz .LBB0_769
	s_mov_b64 s[20:21], 0

.LBB0_781:
	s_and_b32 s34, s28, 0xff
	s_mov_b64 s[30:31], -1
	s_cmp_lg_u32 s34, 0
	s_mov_b64 s[36:37], -1
	s_nop 0
	s_cbranch_scc1 .LBB0_784
	v_readlane_b32 s6, v252, 10
	v_readlane_b32 s7, v252, 11
	s_nop 4
	global_load_dword v0, v189, s[6:7] sc1
	s_waitcnt vmcnt(0)
	v_cmp_eq_u32_e32 vcc, 0, v0
	s_cbranch_vccnz .LBB0_786
	s_mov_b64 s[36:37], 0
	s_mov_b64 s[34:35], -1
